# lean4 + counted vmcnt waits per chunk in the FFN-down/W_out epilogue (residual loads no longer drained with vmcnt(0))
# speedup vs baseline: 1.0012x; 1.0012x over previous
; __device__ __forceinline__ void unpack8(const v4u r, float* x) { x[0] = bflo(r.x); x[1] = bfhi(r.x); x[2] = bflo(r.y); x[3] = bfhi(r.y); x[4] = bflo(r.z); x[5] = bfhi(r.z); x[6] = bflo(r.w); x[7] = bfhi(r.w); }
; __device__ __forceinline__ v4u pack8(const float* x) { v4u o; o.x = pk2(x[0], x[1]); o.y = pk2(x[2], x[3]); o.z = pk2(x[4], x[5]); o.w = pk2(x[6], x[7]); return o; }
; __device__ __forceinline__ float shx_(float v, int lane, int o) { return shl_(v, lane ^ o); }
; __device__ __forceinline__ size_t tl(int row, int col, int K) { return (size_t)(row >> 8) * ((size_t)256 * K) + (size_t)(col >> 6) * (256 * 64) + (size_t)((row & 255) * 64 + (col & 63)); }
;     __device__ __forceinline__ void operator()(const f32x4 (&acc)[2][2][4][2], const Unit& u, int wr, int wc, int, int) const {
;         int t_ = threadIdx.x; asm volatile("" : "+v"(t_)); const int fr = t_ & 15, fq = (t_ >> 4) & 3;
;         const int row0 = u.pm * BM + wr * 64 + fr, col0 = u.pn * BM + wc * 32 + 8 * fq;
;         u32x4 old[2][4][2];
; #pragma unroll
;         for (int ai = 0; ai < 2; ++ai)
; #pragma unroll
;             for (int m = 0; m < 4; ++m)
; #pragma unroll
;                 for (int bj = 0; bj < 2; ++bj) old[ai][m][bj] = *(const u32x4*)(xb + tl(row0 + ai * HALF + m * 16, col0 + bj * HALF, DM));
;         asm volatile("" ::: "memory");
; #pragma unroll
;         for (int ai = 0; ai < 2; ++ai)
; #pragma unroll
;             for (int m = 0; m < 4; ++m) {
;                 const int row = row0 + ai * HALF + m * 16; float ss = 0.f;
; #pragma unroll
;                 for (int bj = 0; bj < 2; ++bj) {
;                     float b[8], v[8]; unpack8(old[ai][m][bj], b);
; #pragma unroll
;                     for (int n = 0; n < 2; ++n)
; #pragma unroll
;                         for (int i = 0; i < 4; ++i) { const float t = b[n * 4 + i] + acc[ai][bj][m][n][i] * scale; v[n * 4 + i] = t; ss += t * t; }
;                     *(u32x4*)(xb + tl(row, col0 + bj * HALF, DM)) = pack8(v);
;                 }
;                 { const int ln = fq * 16 + fr; ss += shx_(ss, ln, 16); ss += shx_(ss, ln, 32); }
;                 if (fq == 0) ssp[(size_t)row * 16 + u.pn * 4 + wc] = ss;
;             }
.LBB0_1325:
	s_lshl_b32 s16, s40, 8
	v_mov_b32_e32 v201, v230
	s_add_i32 s16, s16, s54
	s_lshl_b32 s17, s30, 8
	v_and_or_b32 v200, v201, 15, s16
	s_ashr_i32 s16, s16, 8
	s_or_b32 s18, s17, s55
	s_ashr_i32 s17, s16, 31
	v_bfe_u32 v203, v201, 4, 2
	s_lshl_b64 s[64:65], s[16:17], 19
	v_lshl_or_b32 v210, v203, 3, s61
	v_lshlrev_b32_e32 v80, 6, v200
	s_add_u32 s16, s8, s64
	v_and_or_b32 v80, v80, s84, v210
	s_addc_u32 s17, s9, s65
	s_ashr_i32 s20, s18, 6
	s_ashr_i32 s21, s20, 31
	v_lshlrev_b32_e32 v220, 1, v80
	s_lshl_b64 s[18:19], s[20:21], 15
	v_lshl_add_u64 v[80:81], s[16:17], 0, v[220:221]
	v_lshl_add_u64 v[82:83], v[80:81], 0, s[18:19]
	global_load_dwordx4 v[212:215], v[82:83], off
	global_load_dwordx4 v[180:183], v[82:83], off offset:2048
	s_or_b32 s16, s20, 2
	s_ashr_i32 s17, s16, 31
	s_lshl_b64 s[20:21], s[16:17], 15
	v_lshl_add_u64 v[84:85], v[80:81], 0, s[20:21]
	global_load_dwordx4 v[216:219], v[84:85], off
	v_add_u32_e32 v202, 0x80, v200
	v_ashrrev_i32_e32 v86, 8, v202
	v_lshlrev_b32_e32 v104, 6, v202
	v_ashrrev_i32_e32 v87, 31, v86
	v_and_or_b32 v104, v104, s84, v210
	v_lshlrev_b64 v[198:199], 19, v[86:87]
	v_mov_b32_e32 v205, v221
	v_lshlrev_b32_e32 v204, 1, v104
	v_lshl_add_u64 v[86:87], s[8:9], 0, v[198:199]
	s_mov_b64 s[16:17], 0x1000
	s_mov_b64 s[66:67], 0x1800
	v_lshl_add_u64 v[86:87], v[86:87], 0, v[204:205]
	v_lshl_add_u64 v[104:105], v[80:81], 0, s[16:17]
	v_lshl_add_u64 v[80:81], v[80:81], 0, s[66:67]
	v_lshl_add_u64 v[128:129], v[86:87], 0, s[16:17]
	v_lshl_add_u64 v[106:107], v[104:105], 0, s[18:19]
	v_lshl_add_u64 v[108:109], v[80:81], 0, s[18:19]
	v_lshl_add_u64 v[110:111], v[86:87], 0, s[18:19]
	v_lshl_add_u64 v[130:131], v[86:87], 0, s[66:67]
	v_lshl_add_u64 v[82:83], v[104:105], 0, s[20:21]
	v_lshl_add_u64 v[80:81], v[80:81], 0, s[20:21]
	v_lshl_add_u64 v[86:87], v[86:87], 0, s[20:21]
	v_lshl_add_u64 v[104:105], v[128:129], 0, s[18:19]
	global_load_dwordx4 v[156:159], v[110:111], off
	global_load_dwordx4 v[136:139], v[110:111], off offset:2048
	v_lshl_add_u64 v[208:209], v[128:129], 0, s[20:21]
	v_lshl_add_u64 v[222:223], v[130:131], 0, s[18:19]
	v_lshl_add_u64 v[224:225], v[130:131], 0, s[20:21]
	global_load_dwordx4 v[176:179], v[84:85], off offset:2048
	global_load_dwordx4 v[172:175], v[106:107], off
	global_load_dwordx4 v[168:171], v[82:83], off
	global_load_dwordx4 v[164:167], v[108:109], off
	global_load_dwordx4 v[160:163], v[80:81], off
	global_load_dwordx4 v[152:155], v[86:87], off
	global_load_dwordx4 v[128:131], v[86:87], off offset:2048
	s_nop 0
	global_load_dwordx4 v[108:111], v[104:105], off
	s_nop 0
	global_load_dwordx4 v[104:107], v[208:209], off
	global_load_dwordx4 v[84:87], v[222:223], off
	global_load_dwordx4 v[80:83], v[224:225], off
	s_lshl_b32 s16, s30, 2
	v_lshlrev_b32_e32 v201, 2, v201
	s_ashr_i32 s17, s16, 31
	v_bitop3_b32 v209, v201, 64, v244 bitop3:0x6c
	v_bitop3_b32 v208, v201, s90, v244 bitop3:0x6c
	s_add_u32 s18, s8, s18
	s_addc_u32 s19, s9, s19
	s_add_u32 s20, s8, s20
	s_addc_u32 s21, s9, s21
	v_cmp_eq_u32_e32 vcc, 0, v203
	s_waitcnt vmcnt(13)
	v_lshlrev_b32_e32 v222, 16, v212
	v_and_b32_e32 v223, 0xffff0000, v212
	v_lshlrev_b32_e32 v212, 16, v213
	v_and_b32_e32 v213, 0xffff0000, v213
	v_pk_fma_f32 v[148:149], v[192:193], v[148:149], v[222:223]
	v_lshlrev_b32_e32 v224, 16, v214
	v_and_b32_e32 v225, 0xffff0000, v214
	v_pk_fma_f32 v[150:151], v[192:193], v[150:151], v[212:213]
	v_pk_mul_f32 v[222:223], v[148:149], v[148:149]
	v_pk_fma_f32 v[212:213], v[192:193], v[144:145], v[224:225]
	v_pk_mul_f32 v[224:225], v[150:151], v[150:151]
	v_add_f32_e32 v201, v222, v223
	v_lshlrev_b32_e32 v214, 16, v215
	v_and_b32_e32 v215, 0xffff0000, v215
	v_add_f32_e32 v201, v224, v201
	v_pk_fma_f32 v[214:215], v[192:193], v[146:147], v[214:215]
	v_pk_mul_f32 v[226:227], v[212:213], v[212:213]
	v_cvt_pk_bf16_f32 v144, v148, v149
	v_lshl_add_u64 v[148:149], s[18:19], 0, v[220:221]
	v_add_f32_e32 v201, v225, v201
	v_cvt_pk_bf16_f32 v145, v150, v151
	v_cvt_pk_bf16_f32 v146, v212, v213
	v_cvt_pk_bf16_f32 v147, v214, v215
	v_lshl_add_u64 v[148:149], v[148:149], 0, s[64:65]
	v_add_f32_e32 v201, v226, v201
	v_pk_mul_f32 v[228:229], v[214:215], v[214:215]
	global_store_dwordx4 v[148:149], v[144:147], off
	v_add_f32_e32 v201, v227, v201
	v_add_f32_e32 v201, v228, v201
	v_lshlrev_b32_e32 v144, 16, v216
	v_and_b32_e32 v145, 0xffff0000, v216
	v_pk_fma_f32 v[140:141], v[192:193], v[140:141], v[144:145]
	v_lshlrev_b32_e32 v146, 16, v217
	v_pk_mul_f32 v[144:145], v[140:141], v[140:141]
	v_and_b32_e32 v147, 0xffff0000, v217
	v_add_f32_e32 v201, v229, v201
	v_pk_fma_f32 v[142:143], v[192:193], v[142:143], v[146:147]
	v_add_f32_e32 v144, v144, v201
	v_pk_mul_f32 v[146:147], v[142:143], v[142:143]
	v_lshlrev_b32_e32 v148, 16, v218
	v_and_b32_e32 v149, 0xffff0000, v218
	v_add_f32_e32 v144, v145, v144
	v_pk_fma_f32 v[132:133], v[192:193], v[132:133], v[148:149]
	v_add_f32_e32 v144, v146, v144
	v_pk_mul_f32 v[148:149], v[132:133], v[132:133]
	v_lshlrev_b32_e32 v150, 16, v219
	v_and_b32_e32 v151, 0xffff0000, v219
	v_add_f32_e32 v144, v147, v144
	v_pk_fma_f32 v[134:135], v[192:193], v[134:135], v[150:151]
	v_add_f32_e32 v144, v148, v144
	v_pk_mul_f32 v[150:151], v[134:135], v[134:135]
	v_add_f32_e32 v144, v149, v144
	v_add_f32_e32 v144, v150, v144
	v_add_f32_e32 v144, v151, v144
	ds_bpermute_b32 v145, v209, v144
	v_cvt_pk_bf16_f32 v140, v140, v141
	v_cvt_pk_bf16_f32 v141, v142, v143
	v_cvt_pk_bf16_f32 v142, v132, v133
	v_cvt_pk_bf16_f32 v143, v134, v135
	s_waitcnt lgkmcnt(0)
	v_add_f32_e32 v132, v144, v145
	ds_bpermute_b32 v133, v208, v132
	v_lshl_add_u64 v[134:135], s[20:21], 0, v[220:221]
	v_lshl_add_u64 v[134:135], v[134:135], 0, s[64:65]
	global_store_dwordx4 v[134:135], v[140:143], off
	s_and_saveexec_b64 s[66:67], vcc
	s_cbranch_execz .LBB0_1327
	v_ashrrev_i32_e32 v201, 31, v200
	v_lshlrev_b64 v[134:135], 6, v[200:201]
	v_lshl_add_u64 v[134:135], s[10:11], 0, v[134:135]
	v_lshl_add_u64 v[134:135], s[16:17], 2, v[134:135]
	s_lshl_b32 s30, s52, 2
	v_lshl_add_u64 v[134:135], v[134:135], 0, s[30:31]
	s_waitcnt lgkmcnt(0)
	v_add_f32_e32 v132, v132, v133
	global_store_dword v[134:135], v132, off
; __device__ __forceinline__ void unpack8(const v4u r, float* x) { x[0] = bflo(r.x); x[1] = bfhi(r.x); x[2] = bflo(r.y); x[3] = bfhi(r.y); x[4] = bflo(r.z); x[5] = bfhi(r.z); x[6] = bflo(r.w); x[7] = bfhi(r.w); }
; __device__ __forceinline__ v4u pack8(const float* x) { v4u o; o.x = pk2(x[0], x[1]); o.y = pk2(x[2], x[3]); o.z = pk2(x[4], x[5]); o.w = pk2(x[6], x[7]); return o; }
; __device__ __forceinline__ float shx_(float v, int lane, int o) { return shl_(v, lane ^ o); }
; __device__ __forceinline__ size_t tl(int row, int col, int K) { return (size_t)(row >> 8) * ((size_t)256 * K) + (size_t)(col >> 6) * (256 * 64) + (size_t)((row & 255) * 64 + (col & 63)); }
;     __device__ __forceinline__ void operator()(const f32x4 (&acc)[2][2][4][2], const Unit& u, int wr, int wc, int, int) const {
;     ...
;         for (int ai = 0; ai < 2; ++ai)
; #pragma unroll
;             for (int m = 0; m < 4; ++m) {
;                 const int row = row0 + ai * HALF + m * 16; float ss = 0.f;
; #pragma unroll
;                 for (int bj = 0; bj < 2; ++bj) {
;                     float b[8], v[8]; unpack8(old[ai][m][bj], b);
; #pragma unroll
;                     for (int n = 0; n < 2; ++n)
; #pragma unroll
;                         for (int i = 0; i < 4; ++i) { const float t = b[n * 4 + i] + acc[ai][bj][m][n][i] * scale; v[n * 4 + i] = t; ss += t * t; }
;                     *(u32x4*)(xb + tl(row, col0 + bj * HALF, DM)) = pack8(v);
;                 }
;                 { const int ln = fq * 16 + fr; ss += shx_(ss, ln, 16); ss += shx_(ss, ln, 32); }
;                 if (fq == 0) ssp[(size_t)row * 16 + u.pn * 4 + wc] = ss;
;             }
.LBB0_1327:
	s_or_b64 exec, exec, s[66:67]
	s_waitcnt vmcnt(12)
	v_or_b32_e32 v132, 16, v200
	v_lshlrev_b32_e32 v134, 16, v180
	v_and_b32_e32 v135, 0xffff0000, v180
	s_waitcnt lgkmcnt(0)
	v_lshlrev_b32_e32 v133, 6, v132
	v_pk_fma_f32 v[124:125], v[192:193], v[124:125], v[134:135]
	v_lshlrev_b32_e32 v140, 16, v181
	v_and_b32_e32 v141, 0xffff0000, v181
	v_and_or_b32 v133, v133, s88, v210
	v_pk_mul_f32 v[134:135], v[124:125], v[124:125]
	v_pk_fma_f32 v[126:127], v[192:193], v[126:127], v[140:141]
	v_lshlrev_b32_e32 v142, 16, v182
	v_pk_mul_f32 v[140:141], v[126:127], v[126:127]
	v_and_b32_e32 v143, 0xffff0000, v182
	v_lshlrev_b32_e32 v220, 1, v133
	v_add_f32_e32 v133, v134, v135
	v_pk_fma_f32 v[142:143], v[192:193], v[120:121], v[142:143]
	v_lshlrev_b32_e32 v120, 16, v183
	v_and_b32_e32 v121, 0xffff0000, v183
	v_add_f32_e32 v133, v140, v133
	v_pk_mul_f32 v[144:145], v[142:143], v[142:143]
	v_pk_fma_f32 v[146:147], v[192:193], v[122:123], v[120:121]
	v_cvt_pk_bf16_f32 v120, v124, v125
	v_lshl_add_u64 v[124:125], s[18:19], 0, v[220:221]
	v_add_f32_e32 v133, v141, v133
	v_cvt_pk_bf16_f32 v121, v126, v127
	v_cvt_pk_bf16_f32 v122, v142, v143
	v_cvt_pk_bf16_f32 v123, v146, v147
	v_lshl_add_u64 v[124:125], v[124:125], 0, s[64:65]
	v_add_f32_e32 v133, v144, v133
	v_pk_mul_f32 v[148:149], v[146:147], v[146:147]
	global_store_dwordx4 v[124:125], v[120:123], off
	v_add_f32_e32 v133, v145, v133
	v_add_f32_e32 v133, v148, v133
	v_lshlrev_b32_e32 v120, 16, v176
	v_and_b32_e32 v121, 0xffff0000, v176
	v_pk_fma_f32 v[116:117], v[192:193], v[116:117], v[120:121]
	v_lshlrev_b32_e32 v122, 16, v177
	v_pk_mul_f32 v[120:121], v[116:117], v[116:117]
	v_and_b32_e32 v123, 0xffff0000, v177
	v_add_f32_e32 v133, v149, v133
	v_pk_fma_f32 v[118:119], v[192:193], v[118:119], v[122:123]
	v_add_f32_e32 v120, v120, v133
	v_pk_mul_f32 v[122:123], v[118:119], v[118:119]
	v_lshlrev_b32_e32 v124, 16, v178
	v_and_b32_e32 v125, 0xffff0000, v178
	v_add_f32_e32 v120, v121, v120
	v_pk_fma_f32 v[124:125], v[192:193], v[112:113], v[124:125]
	v_add_f32_e32 v120, v122, v120
	v_pk_mul_f32 v[112:113], v[124:125], v[124:125]
	v_lshlrev_b32_e32 v126, 16, v179
	v_and_b32_e32 v127, 0xffff0000, v179
	v_add_f32_e32 v120, v123, v120
	v_pk_fma_f32 v[126:127], v[192:193], v[114:115], v[126:127]
	v_add_f32_e32 v112, v112, v120
	v_pk_mul_f32 v[114:115], v[126:127], v[126:127]
	v_add_f32_e32 v112, v113, v112
	v_add_f32_e32 v112, v114, v112
	v_add_f32_e32 v120, v115, v112
	v_cvt_pk_bf16_f32 v112, v116, v117
	v_lshl_add_u64 v[116:117], s[20:21], 0, v[220:221]
	v_cvt_pk_bf16_f32 v113, v118, v119
	v_cvt_pk_bf16_f32 v114, v124, v125
	v_cvt_pk_bf16_f32 v115, v126, v127
	v_lshl_add_u64 v[116:117], v[116:117], 0, s[64:65]
	global_store_dwordx4 v[116:117], v[112:115], off
	ds_bpermute_b32 v112, v209, v120
	s_waitcnt lgkmcnt(0)
	v_add_f32_e32 v112, v120, v112
	ds_bpermute_b32 v113, v208, v112
	s_and_saveexec_b64 s[66:67], vcc
	s_cbranch_execz .LBB0_1329
	v_ashrrev_i32_e32 v133, 31, v132
	v_lshlrev_b64 v[114:115], 6, v[132:133]
	v_lshl_add_u64 v[114:115], s[10:11], 0, v[114:115]
	v_lshl_add_u64 v[114:115], s[16:17], 2, v[114:115]
	s_lshl_b32 s30, s52, 2
	v_lshl_add_u64 v[114:115], v[114:115], 0, s[30:31]
	s_waitcnt lgkmcnt(0)
	v_add_f32_e32 v112, v112, v113
	global_store_dword v[114:115], v112, off
.LBB0_1329:
	s_or_b64 exec, exec, s[66:67]
	s_waitcnt vmcnt(12)
	v_or_b32_e32 v112, 32, v200
	v_lshlrev_b32_e32 v114, 16, v172
	v_and_b32_e32 v115, 0xffff0000, v172
	s_waitcnt lgkmcnt(0)
	v_lshlrev_b32_e32 v113, 6, v112
	v_pk_fma_f32 v[100:101], v[192:193], v[100:101], v[114:115]
	v_lshlrev_b32_e32 v116, 16, v173
	v_and_b32_e32 v117, 0xffff0000, v173
	v_and_or_b32 v113, v113, s89, v210
	v_pk_mul_f32 v[114:115], v[100:101], v[100:101]
	v_pk_fma_f32 v[102:103], v[192:193], v[102:103], v[116:117]
	v_lshlrev_b32_e32 v118, 16, v174
	v_pk_mul_f32 v[116:117], v[102:103], v[102:103]
	v_and_b32_e32 v119, 0xffff0000, v174
	v_lshlrev_b32_e32 v220, 1, v113
	v_add_f32_e32 v113, v114, v115
	v_pk_fma_f32 v[118:119], v[192:193], v[96:97], v[118:119]
	v_lshlrev_b32_e32 v96, 16, v175
	v_and_b32_e32 v97, 0xffff0000, v175
	v_add_f32_e32 v113, v116, v113
	v_pk_mul_f32 v[120:121], v[118:119], v[118:119]
	v_pk_fma_f32 v[122:123], v[192:193], v[98:99], v[96:97]
	v_cvt_pk_bf16_f32 v96, v100, v101
	v_lshl_add_u64 v[100:101], s[18:19], 0, v[220:221]
	v_add_f32_e32 v113, v117, v113
	v_cvt_pk_bf16_f32 v97, v102, v103
	v_cvt_pk_bf16_f32 v98, v118, v119
	v_cvt_pk_bf16_f32 v99, v122, v123
	v_lshl_add_u64 v[100:101], v[100:101], 0, s[64:65]
	v_add_f32_e32 v113, v120, v113
	v_pk_mul_f32 v[124:125], v[122:123], v[122:123]
	global_store_dwordx4 v[100:101], v[96:99], off
	v_add_f32_e32 v113, v121, v113
	v_add_f32_e32 v113, v124, v113
	v_lshlrev_b32_e32 v96, 16, v168
	v_and_b32_e32 v97, 0xffff0000, v168
	v_pk_fma_f32 v[92:93], v[192:193], v[92:93], v[96:97]
	v_lshlrev_b32_e32 v98, 16, v169
	v_pk_mul_f32 v[96:97], v[92:93], v[92:93]
	v_and_b32_e32 v99, 0xffff0000, v169
	v_add_f32_e32 v113, v125, v113
	v_pk_fma_f32 v[94:95], v[192:193], v[94:95], v[98:99]
	v_add_f32_e32 v96, v96, v113
	v_pk_mul_f32 v[98:99], v[94:95], v[94:95]
	v_lshlrev_b32_e32 v100, 16, v170
	v_and_b32_e32 v101, 0xffff0000, v170
	v_add_f32_e32 v96, v97, v96
	v_pk_fma_f32 v[100:101], v[192:193], v[88:89], v[100:101]
	v_add_f32_e32 v96, v98, v96
	v_pk_mul_f32 v[88:89], v[100:101], v[100:101]
	v_lshlrev_b32_e32 v102, 16, v171
	v_and_b32_e32 v103, 0xffff0000, v171
	v_add_f32_e32 v96, v99, v96
	v_pk_fma_f32 v[102:103], v[192:193], v[90:91], v[102:103]
	v_add_f32_e32 v88, v88, v96
	v_pk_mul_f32 v[90:91], v[102:103], v[102:103]
	v_add_f32_e32 v88, v89, v88
	v_add_f32_e32 v88, v90, v88
	v_add_f32_e32 v96, v91, v88
	v_cvt_pk_bf16_f32 v88, v92, v93
	v_lshl_add_u64 v[92:93], s[20:21], 0, v[220:221]
	v_cvt_pk_bf16_f32 v89, v94, v95
	v_cvt_pk_bf16_f32 v90, v100, v101
	v_cvt_pk_bf16_f32 v91, v102, v103
	v_lshl_add_u64 v[92:93], v[92:93], 0, s[64:65]
	global_store_dwordx4 v[92:93], v[88:91], off
	ds_bpermute_b32 v88, v209, v96
	s_waitcnt lgkmcnt(0)
	v_add_f32_e32 v88, v96, v88
	ds_bpermute_b32 v89, v208, v88
	s_and_saveexec_b64 s[66:67], vcc
	s_cbranch_execz .LBB0_1331
	v_ashrrev_i32_e32 v113, 31, v112
	v_lshlrev_b64 v[90:91], 6, v[112:113]
	v_lshl_add_u64 v[90:91], s[10:11], 0, v[90:91]
	v_lshl_add_u64 v[90:91], s[16:17], 2, v[90:91]
	s_lshl_b32 s30, s52, 2
	v_lshl_add_u64 v[90:91], v[90:91], 0, s[30:31]
	s_waitcnt lgkmcnt(0)
	v_add_f32_e32 v88, v88, v89
	global_store_dword v[90:91], v88, off
; __device__ __forceinline__ void unpack8(const v4u r, float* x) { x[0] = bflo(r.x); x[1] = bfhi(r.x); x[2] = bflo(r.y); x[3] = bfhi(r.y); x[4] = bflo(r.z); x[5] = bfhi(r.z); x[6] = bflo(r.w); x[7] = bfhi(r.w); }
; __device__ __forceinline__ v4u pack8(const float* x) { v4u o; o.x = pk2(x[0], x[1]); o.y = pk2(x[2], x[3]); o.z = pk2(x[4], x[5]); o.w = pk2(x[6], x[7]); return o; }
; __device__ __forceinline__ float shx_(float v, int lane, int o) { return shl_(v, lane ^ o); }
; __device__ __forceinline__ size_t tl(int row, int col, int K) { return (size_t)(row >> 8) * ((size_t)256 * K) + (size_t)(col >> 6) * (256 * 64) + (size_t)((row & 255) * 64 + (col & 63)); }
;     __device__ __forceinline__ void operator()(const f32x4 (&acc)[2][2][4][2], const Unit& u, int wr, int wc, int, int) const {
;     ...
;         for (int ai = 0; ai < 2; ++ai)
; #pragma unroll
;             for (int m = 0; m < 4; ++m) {
;                 const int row = row0 + ai * HALF + m * 16; float ss = 0.f;
; #pragma unroll
;                 for (int bj = 0; bj < 2; ++bj) {
;                     float b[8], v[8]; unpack8(old[ai][m][bj], b);
; #pragma unroll
;                     for (int n = 0; n < 2; ++n)
; #pragma unroll
;                         for (int i = 0; i < 4; ++i) { const float t = b[n * 4 + i] + acc[ai][bj][m][n][i] * scale; v[n * 4 + i] = t; ss += t * t; }
;                     *(u32x4*)(xb + tl(row, col0 + bj * HALF, DM)) = pack8(v);
;                 }
;                 { const int ln = fq * 16 + fr; ss += shx_(ss, ln, 16); ss += shx_(ss, ln, 32); }
;                 if (fq == 0) ssp[(size_t)row * 16 + u.pn * 4 + wc] = ss;
;             }
.LBB0_1331:
	s_or_b64 exec, exec, s[66:67]
	s_waitcnt vmcnt(12)
	v_or_b32_e32 v88, 48, v200
	v_lshlrev_b32_e32 v90, 16, v164
	v_and_b32_e32 v91, 0xffff0000, v164
	s_waitcnt lgkmcnt(0)
	v_lshlrev_b32_e32 v89, 6, v88
	v_pk_fma_f32 v[76:77], v[192:193], v[76:77], v[90:91]
	v_lshlrev_b32_e32 v92, 16, v165
	v_and_b32_e32 v93, 0xffff0000, v165
	v_and_or_b32 v89, v89, s86, v210
	v_pk_mul_f32 v[90:91], v[76:77], v[76:77]
	v_pk_fma_f32 v[78:79], v[192:193], v[78:79], v[92:93]
	v_lshlrev_b32_e32 v94, 16, v166
	v_pk_mul_f32 v[92:93], v[78:79], v[78:79]
	v_and_b32_e32 v95, 0xffff0000, v166
	v_lshlrev_b32_e32 v220, 1, v89
	v_add_f32_e32 v89, v90, v91
	v_pk_fma_f32 v[94:95], v[192:193], v[72:73], v[94:95]
	v_lshlrev_b32_e32 v72, 16, v167
	v_and_b32_e32 v73, 0xffff0000, v167
	v_add_f32_e32 v89, v92, v89
	v_pk_mul_f32 v[96:97], v[94:95], v[94:95]
	v_pk_fma_f32 v[98:99], v[192:193], v[74:75], v[72:73]
	v_cvt_pk_bf16_f32 v72, v76, v77
	v_lshl_add_u64 v[76:77], s[18:19], 0, v[220:221]
	v_add_f32_e32 v89, v93, v89
	v_cvt_pk_bf16_f32 v73, v78, v79
	v_cvt_pk_bf16_f32 v74, v94, v95
	v_cvt_pk_bf16_f32 v75, v98, v99
	v_lshl_add_u64 v[76:77], v[76:77], 0, s[64:65]
	v_add_f32_e32 v89, v96, v89
	v_pk_mul_f32 v[100:101], v[98:99], v[98:99]
	global_store_dwordx4 v[76:77], v[72:75], off
	v_add_f32_e32 v89, v97, v89
	v_add_f32_e32 v89, v100, v89
	v_lshlrev_b32_e32 v72, 16, v160
	v_and_b32_e32 v73, 0xffff0000, v160
	v_pk_fma_f32 v[68:69], v[192:193], v[68:69], v[72:73]
	v_lshlrev_b32_e32 v74, 16, v161
	v_pk_mul_f32 v[72:73], v[68:69], v[68:69]
	v_and_b32_e32 v75, 0xffff0000, v161
	v_add_f32_e32 v89, v101, v89
	v_pk_fma_f32 v[70:71], v[192:193], v[70:71], v[74:75]
	v_add_f32_e32 v72, v72, v89
	v_pk_mul_f32 v[74:75], v[70:71], v[70:71]
	v_lshlrev_b32_e32 v76, 16, v162
	v_and_b32_e32 v77, 0xffff0000, v162
	v_add_f32_e32 v72, v73, v72
	v_pk_fma_f32 v[76:77], v[192:193], v[64:65], v[76:77]
	v_add_f32_e32 v72, v74, v72
	v_pk_mul_f32 v[64:65], v[76:77], v[76:77]
	v_lshlrev_b32_e32 v78, 16, v163
	v_and_b32_e32 v79, 0xffff0000, v163
	v_add_f32_e32 v72, v75, v72
	v_pk_fma_f32 v[78:79], v[192:193], v[66:67], v[78:79]
	v_add_f32_e32 v64, v64, v72
	v_pk_mul_f32 v[66:67], v[78:79], v[78:79]
	v_add_f32_e32 v64, v65, v64
	v_add_f32_e32 v64, v66, v64
	v_add_f32_e32 v72, v67, v64
	v_cvt_pk_bf16_f32 v64, v68, v69
	v_lshl_add_u64 v[68:69], s[20:21], 0, v[220:221]
	v_cvt_pk_bf16_f32 v65, v70, v71
	v_cvt_pk_bf16_f32 v66, v76, v77
	v_cvt_pk_bf16_f32 v67, v78, v79
	v_lshl_add_u64 v[68:69], v[68:69], 0, s[64:65]
	global_store_dwordx4 v[68:69], v[64:67], off
	ds_bpermute_b32 v64, v209, v72
	s_waitcnt lgkmcnt(0)
	v_add_f32_e32 v64, v72, v64
	ds_bpermute_b32 v65, v208, v64
	s_and_saveexec_b64 s[64:65], vcc
	s_cbranch_execz .LBB0_1333
	v_ashrrev_i32_e32 v89, 31, v88
	v_lshlrev_b64 v[66:67], 6, v[88:89]
	v_lshl_add_u64 v[66:67], s[10:11], 0, v[66:67]
	v_lshl_add_u64 v[66:67], s[16:17], 2, v[66:67]
	s_lshl_b32 s30, s52, 2
	v_lshl_add_u64 v[66:67], v[66:67], 0, s[30:31]
	s_waitcnt lgkmcnt(0)
	v_add_f32_e32 v64, v64, v65
	global_store_dword v[66:67], v64, off
.LBB0_1333:
	s_or_b64 exec, exec, s[64:65]
	s_waitcnt vmcnt(13)
	v_lshlrev_b32_e32 v64, 16, v156
	s_waitcnt lgkmcnt(0)
	v_and_b32_e32 v65, 0xffff0000, v156
	v_pk_fma_f32 v[60:61], v[192:193], v[60:61], v[64:65]
	v_lshlrev_b32_e32 v66, 16, v157
	v_and_b32_e32 v67, 0xffff0000, v157
	v_pk_mul_f32 v[64:65], v[60:61], v[60:61]
	v_pk_fma_f32 v[62:63], v[192:193], v[62:63], v[66:67]
	v_lshlrev_b32_e32 v68, 16, v158
	v_pk_mul_f32 v[66:67], v[62:63], v[62:63]
	v_and_b32_e32 v69, 0xffff0000, v158
	v_add_f32_e32 v64, v64, v65
	v_pk_fma_f32 v[68:69], v[192:193], v[56:57], v[68:69]
	v_lshlrev_b32_e32 v56, 16, v159
	v_and_b32_e32 v57, 0xffff0000, v159
	v_mov_b32_e32 v205, v221
	v_add_f32_e32 v64, v66, v64
	v_pk_mul_f32 v[70:71], v[68:69], v[68:69]
	v_pk_fma_f32 v[72:73], v[192:193], v[58:59], v[56:57]
	v_cvt_pk_bf16_f32 v56, v60, v61
	v_lshl_add_u64 v[60:61], s[18:19], 0, v[204:205]
	v_add_f32_e32 v64, v67, v64
	v_cvt_pk_bf16_f32 v57, v62, v63
	v_cvt_pk_bf16_f32 v58, v68, v69
	v_cvt_pk_bf16_f32 v59, v72, v73
	v_lshl_add_u64 v[60:61], v[60:61], 0, v[198:199]
	v_add_f32_e32 v64, v70, v64
	v_pk_mul_f32 v[74:75], v[72:73], v[72:73]
	global_store_dwordx4 v[60:61], v[56:59], off
	v_add_f32_e32 v64, v71, v64
	v_add_f32_e32 v64, v74, v64
	v_lshlrev_b32_e32 v56, 16, v152
	v_and_b32_e32 v57, 0xffff0000, v152
	v_pk_fma_f32 v[52:53], v[192:193], v[52:53], v[56:57]
	v_lshlrev_b32_e32 v58, 16, v153
	v_pk_mul_f32 v[56:57], v[52:53], v[52:53]
	v_and_b32_e32 v59, 0xffff0000, v153
	v_add_f32_e32 v64, v75, v64
	v_pk_fma_f32 v[54:55], v[192:193], v[54:55], v[58:59]
	v_add_f32_e32 v56, v56, v64
	v_pk_mul_f32 v[58:59], v[54:55], v[54:55]
	v_lshlrev_b32_e32 v60, 16, v154
	v_and_b32_e32 v61, 0xffff0000, v154
	v_add_f32_e32 v56, v57, v56
	v_pk_fma_f32 v[60:61], v[192:193], v[48:49], v[60:61]
	v_add_f32_e32 v56, v58, v56
	v_pk_mul_f32 v[48:49], v[60:61], v[60:61]
	v_lshlrev_b32_e32 v62, 16, v155
	v_and_b32_e32 v63, 0xffff0000, v155
	v_add_f32_e32 v56, v59, v56
	v_pk_fma_f32 v[62:63], v[192:193], v[50:51], v[62:63]
	v_add_f32_e32 v48, v48, v56
	v_pk_mul_f32 v[50:51], v[62:63], v[62:63]
	v_add_f32_e32 v48, v49, v48
	v_add_f32_e32 v48, v50, v48
	v_add_f32_e32 v56, v51, v48
	v_cvt_pk_bf16_f32 v48, v52, v53
	v_lshl_add_u64 v[52:53], s[20:21], 0, v[204:205]
	v_cvt_pk_bf16_f32 v49, v54, v55
	v_cvt_pk_bf16_f32 v50, v60, v61
	v_cvt_pk_bf16_f32 v51, v62, v63
	v_lshl_add_u64 v[52:53], v[52:53], 0, v[198:199]
	global_store_dwordx4 v[52:53], v[48:51], off
	ds_bpermute_b32 v48, v209, v56
	s_waitcnt lgkmcnt(0)
	v_add_f32_e32 v48, v56, v48
	ds_bpermute_b32 v49, v208, v48
	s_and_saveexec_b64 s[64:65], vcc
	s_cbranch_execz .LBB0_1335
	v_ashrrev_i32_e32 v203, 31, v202
	v_lshlrev_b64 v[50:51], 6, v[202:203]
	v_lshl_add_u64 v[50:51], s[10:11], 0, v[50:51]
	v_lshl_add_u64 v[50:51], s[16:17], 2, v[50:51]
	s_lshl_b32 s30, s52, 2
	v_lshl_add_u64 v[50:51], v[50:51], 0, s[30:31]
	s_waitcnt lgkmcnt(0)
	v_add_f32_e32 v48, v48, v49
	global_store_dword v[50:51], v48, off
; __device__ __forceinline__ void unpack8(const v4u r, float* x) { x[0] = bflo(r.x); x[1] = bfhi(r.x); x[2] = bflo(r.y); x[3] = bfhi(r.y); x[4] = bflo(r.z); x[5] = bfhi(r.z); x[6] = bflo(r.w); x[7] = bfhi(r.w); }
; __device__ __forceinline__ v4u pack8(const float* x) { v4u o; o.x = pk2(x[0], x[1]); o.y = pk2(x[2], x[3]); o.z = pk2(x[4], x[5]); o.w = pk2(x[6], x[7]); return o; }
; __device__ __forceinline__ float shx_(float v, int lane, int o) { return shl_(v, lane ^ o); }
; __device__ __forceinline__ size_t tl(int row, int col, int K) { return (size_t)(row >> 8) * ((size_t)256 * K) + (size_t)(col >> 6) * (256 * 64) + (size_t)((row & 255) * 64 + (col & 63)); }
;     __device__ __forceinline__ void operator()(const f32x4 (&acc)[2][2][4][2], const Unit& u, int wr, int wc, int, int) const {
;     ...
;         for (int ai = 0; ai < 2; ++ai)
; #pragma unroll
;             for (int m = 0; m < 4; ++m) {
;                 const int row = row0 + ai * HALF + m * 16; float ss = 0.f;
; #pragma unroll
;                 for (int bj = 0; bj < 2; ++bj) {
;                     float b[8], v[8]; unpack8(old[ai][m][bj], b);
; #pragma unroll
;                     for (int n = 0; n < 2; ++n)
; #pragma unroll
;                         for (int i = 0; i < 4; ++i) { const float t = b[n * 4 + i] + acc[ai][bj][m][n][i] * scale; v[n * 4 + i] = t; ss += t * t; }
;                     *(u32x4*)(xb + tl(row, col0 + bj * HALF, DM)) = pack8(v);
;                 }
;                 { const int ln = fq * 16 + fr; ss += shx_(ss, ln, 16); ss += shx_(ss, ln, 32); }
;                 if (fq == 0) ssp[(size_t)row * 16 + u.pn * 4 + wc] = ss;
;             }
.LBB0_1335:
	s_or_b64 exec, exec, s[64:65]
	s_waitcnt vmcnt(14)
	v_add_u32_e32 v48, 0x90, v200
	v_lshlrev_b32_e32 v50, 16, v136
	v_and_b32_e32 v51, 0xffff0000, v136
	s_waitcnt lgkmcnt(0)
	v_lshlrev_b32_e32 v49, 6, v48
	v_pk_fma_f32 v[44:45], v[192:193], v[44:45], v[50:51]
	v_lshlrev_b32_e32 v52, 16, v137
	v_and_b32_e32 v53, 0xffff0000, v137
	v_and_or_b32 v49, v49, s88, v210
	v_pk_mul_f32 v[50:51], v[44:45], v[44:45]
	v_pk_fma_f32 v[46:47], v[192:193], v[46:47], v[52:53]
	v_lshlrev_b32_e32 v54, 16, v138
	v_pk_mul_f32 v[52:53], v[46:47], v[46:47]
	v_and_b32_e32 v55, 0xffff0000, v138
	v_lshlrev_b32_e32 v220, 1, v49
	v_add_f32_e32 v49, v50, v51
	v_pk_fma_f32 v[54:55], v[192:193], v[40:41], v[54:55]
	v_lshlrev_b32_e32 v40, 16, v139
	v_and_b32_e32 v41, 0xffff0000, v139
	v_add_f32_e32 v49, v52, v49
	v_pk_mul_f32 v[56:57], v[54:55], v[54:55]
	v_pk_fma_f32 v[58:59], v[192:193], v[42:43], v[40:41]
	v_cvt_pk_bf16_f32 v40, v44, v45
	v_lshl_add_u64 v[44:45], s[18:19], 0, v[220:221]
	v_add_f32_e32 v49, v53, v49
	v_cvt_pk_bf16_f32 v41, v46, v47
	v_cvt_pk_bf16_f32 v42, v54, v55
	v_cvt_pk_bf16_f32 v43, v58, v59
	v_lshl_add_u64 v[44:45], v[44:45], 0, v[198:199]
	v_add_f32_e32 v49, v56, v49
	v_pk_mul_f32 v[60:61], v[58:59], v[58:59]
	global_store_dwordx4 v[44:45], v[40:43], off
	v_add_f32_e32 v49, v57, v49
	v_add_f32_e32 v49, v60, v49
	v_lshlrev_b32_e32 v40, 16, v128
	v_and_b32_e32 v41, 0xffff0000, v128
	v_pk_fma_f32 v[36:37], v[192:193], v[36:37], v[40:41]
	v_lshlrev_b32_e32 v42, 16, v129
	v_pk_mul_f32 v[40:41], v[36:37], v[36:37]
	v_and_b32_e32 v43, 0xffff0000, v129
	v_add_f32_e32 v49, v61, v49
	v_pk_fma_f32 v[38:39], v[192:193], v[38:39], v[42:43]
	v_add_f32_e32 v40, v40, v49
	v_pk_mul_f32 v[42:43], v[38:39], v[38:39]
	v_lshlrev_b32_e32 v44, 16, v130
	v_and_b32_e32 v45, 0xffff0000, v130
	v_add_f32_e32 v40, v41, v40
	v_pk_fma_f32 v[44:45], v[192:193], v[32:33], v[44:45]
	v_add_f32_e32 v40, v42, v40
	v_pk_mul_f32 v[32:33], v[44:45], v[44:45]
	v_lshlrev_b32_e32 v46, 16, v131
	v_and_b32_e32 v47, 0xffff0000, v131
	v_add_f32_e32 v40, v43, v40
	v_pk_fma_f32 v[46:47], v[192:193], v[34:35], v[46:47]
	v_add_f32_e32 v32, v32, v40
	v_pk_mul_f32 v[34:35], v[46:47], v[46:47]
	v_add_f32_e32 v32, v33, v32
	v_add_f32_e32 v32, v34, v32
	v_add_f32_e32 v40, v35, v32
	v_cvt_pk_bf16_f32 v32, v36, v37
	v_lshl_add_u64 v[36:37], s[20:21], 0, v[220:221]
	v_cvt_pk_bf16_f32 v33, v38, v39
	v_cvt_pk_bf16_f32 v34, v44, v45
	v_cvt_pk_bf16_f32 v35, v46, v47
	v_lshl_add_u64 v[36:37], v[36:37], 0, v[198:199]
	global_store_dwordx4 v[36:37], v[32:35], off
	ds_bpermute_b32 v32, v209, v40
	s_waitcnt lgkmcnt(0)
	v_add_f32_e32 v32, v40, v32
	ds_bpermute_b32 v33, v208, v32
	s_and_saveexec_b64 s[64:65], vcc
	s_cbranch_execz .LBB0_1337
	v_ashrrev_i32_e32 v49, 31, v48
	v_lshlrev_b64 v[34:35], 6, v[48:49]
	v_lshl_add_u64 v[34:35], s[10:11], 0, v[34:35]
	v_lshl_add_u64 v[34:35], s[16:17], 2, v[34:35]
	s_lshl_b32 s30, s52, 2
	v_lshl_add_u64 v[34:35], v[34:35], 0, s[30:31]
	s_waitcnt lgkmcnt(0)
	v_add_f32_e32 v32, v32, v33
	global_store_dword v[34:35], v32, off
; __device__ __forceinline__ void unpack8(const v4u r, float* x) { x[0] = bflo(r.x); x[1] = bfhi(r.x); x[2] = bflo(r.y); x[3] = bfhi(r.y); x[4] = bflo(r.z); x[5] = bfhi(r.z); x[6] = bflo(r.w); x[7] = bfhi(r.w); }
; __device__ __forceinline__ v4u pack8(const float* x) { v4u o; o.x = pk2(x[0], x[1]); o.y = pk2(x[2], x[3]); o.z = pk2(x[4], x[5]); o.w = pk2(x[6], x[7]); return o; }
; __device__ __forceinline__ float shx_(float v, int lane, int o) { return shl_(v, lane ^ o); }
; __device__ __forceinline__ size_t tl(int row, int col, int K) { return (size_t)(row >> 8) * ((size_t)256 * K) + (size_t)(col >> 6) * (256 * 64) + (size_t)((row & 255) * 64 + (col & 63)); }
;     __device__ __forceinline__ void operator()(const f32x4 (&acc)[2][2][4][2], const Unit& u, int wr, int wc, int, int) const {
;     ...
;         for (int ai = 0; ai < 2; ++ai)
; #pragma unroll
;             for (int m = 0; m < 4; ++m) {
;                 const int row = row0 + ai * HALF + m * 16; float ss = 0.f;
; #pragma unroll
;                 for (int bj = 0; bj < 2; ++bj) {
;                     float b[8], v[8]; unpack8(old[ai][m][bj], b);
; #pragma unroll
;                     for (int n = 0; n < 2; ++n)
; #pragma unroll
;                         for (int i = 0; i < 4; ++i) { const float t = b[n * 4 + i] + acc[ai][bj][m][n][i] * scale; v[n * 4 + i] = t; ss += t * t; }
;                     *(u32x4*)(xb + tl(row, col0 + bj * HALF, DM)) = pack8(v);
;                 }
;                 { const int ln = fq * 16 + fr; ss += shx_(ss, ln, 16); ss += shx_(ss, ln, 32); }
;                 if (fq == 0) ssp[(size_t)row * 16 + u.pn * 4 + wc] = ss;
;             }
.LBB0_1337:
	s_or_b64 exec, exec, s[64:65]
	s_waitcnt vmcnt(14)
	v_add_u32_e32 v32, 0xa0, v200
	v_lshlrev_b32_e32 v34, 16, v108
	v_and_b32_e32 v35, 0xffff0000, v108
	s_waitcnt lgkmcnt(0)
	v_lshlrev_b32_e32 v33, 6, v32
	v_pk_fma_f32 v[28:29], v[192:193], v[28:29], v[34:35]
	v_lshlrev_b32_e32 v36, 16, v109
	v_and_b32_e32 v37, 0xffff0000, v109
	v_and_or_b32 v33, v33, s89, v210
	v_pk_mul_f32 v[34:35], v[28:29], v[28:29]
	v_pk_fma_f32 v[30:31], v[192:193], v[30:31], v[36:37]
	v_lshlrev_b32_e32 v38, 16, v110
	v_pk_mul_f32 v[36:37], v[30:31], v[30:31]
	v_and_b32_e32 v39, 0xffff0000, v110
	v_lshlrev_b32_e32 v220, 1, v33
	v_add_f32_e32 v33, v34, v35
	v_pk_fma_f32 v[38:39], v[192:193], v[24:25], v[38:39]
	v_lshlrev_b32_e32 v24, 16, v111
	v_and_b32_e32 v25, 0xffff0000, v111
	v_add_f32_e32 v33, v36, v33
	v_pk_mul_f32 v[40:41], v[38:39], v[38:39]
	v_pk_fma_f32 v[42:43], v[192:193], v[26:27], v[24:25]
	v_cvt_pk_bf16_f32 v24, v28, v29
	v_lshl_add_u64 v[28:29], s[18:19], 0, v[220:221]
	v_add_f32_e32 v33, v37, v33
	v_cvt_pk_bf16_f32 v25, v30, v31
	v_cvt_pk_bf16_f32 v26, v38, v39
	v_cvt_pk_bf16_f32 v27, v42, v43
	v_lshl_add_u64 v[28:29], v[28:29], 0, v[198:199]
	v_add_f32_e32 v33, v40, v33
	v_pk_mul_f32 v[44:45], v[42:43], v[42:43]
	global_store_dwordx4 v[28:29], v[24:27], off
	v_add_f32_e32 v33, v41, v33
	v_add_f32_e32 v33, v44, v33
	v_lshlrev_b32_e32 v24, 16, v104
	v_and_b32_e32 v25, 0xffff0000, v104
	v_pk_fma_f32 v[20:21], v[192:193], v[20:21], v[24:25]
	v_lshlrev_b32_e32 v26, 16, v105
	v_pk_mul_f32 v[24:25], v[20:21], v[20:21]
	v_and_b32_e32 v27, 0xffff0000, v105
	v_add_f32_e32 v33, v45, v33
	v_pk_fma_f32 v[22:23], v[192:193], v[22:23], v[26:27]
	v_add_f32_e32 v24, v24, v33
	v_pk_mul_f32 v[26:27], v[22:23], v[22:23]
	v_lshlrev_b32_e32 v28, 16, v106
	v_and_b32_e32 v29, 0xffff0000, v106
	v_add_f32_e32 v24, v25, v24
	v_pk_fma_f32 v[28:29], v[192:193], v[16:17], v[28:29]
	v_add_f32_e32 v24, v26, v24
	v_pk_mul_f32 v[16:17], v[28:29], v[28:29]
	v_lshlrev_b32_e32 v30, 16, v107
	v_and_b32_e32 v31, 0xffff0000, v107
	v_add_f32_e32 v24, v27, v24
	v_pk_fma_f32 v[30:31], v[192:193], v[18:19], v[30:31]
	v_add_f32_e32 v16, v16, v24
	v_pk_mul_f32 v[18:19], v[30:31], v[30:31]
	v_add_f32_e32 v16, v17, v16
	v_add_f32_e32 v16, v18, v16
	v_add_f32_e32 v24, v19, v16
	v_cvt_pk_bf16_f32 v16, v20, v21
	v_lshl_add_u64 v[20:21], s[20:21], 0, v[220:221]
	v_cvt_pk_bf16_f32 v17, v22, v23
	v_cvt_pk_bf16_f32 v18, v28, v29
	v_cvt_pk_bf16_f32 v19, v30, v31
	v_lshl_add_u64 v[20:21], v[20:21], 0, v[198:199]
	global_store_dwordx4 v[20:21], v[16:19], off
	ds_bpermute_b32 v16, v209, v24
	s_waitcnt lgkmcnt(0)
	v_add_f32_e32 v16, v24, v16
	ds_bpermute_b32 v17, v208, v16
	s_and_saveexec_b64 s[64:65], vcc
	s_cbranch_execz .LBB0_1339
	v_ashrrev_i32_e32 v33, 31, v32
	v_lshlrev_b64 v[18:19], 6, v[32:33]
	v_lshl_add_u64 v[18:19], s[10:11], 0, v[18:19]
	v_lshl_add_u64 v[18:19], s[16:17], 2, v[18:19]
	s_lshl_b32 s30, s52, 2
	v_lshl_add_u64 v[18:19], v[18:19], 0, s[30:31]
	s_waitcnt lgkmcnt(0)
	v_add_f32_e32 v16, v16, v17
	global_store_dword v[18:19], v16, off
.LBB0_1339:
	s_or_b64 exec, exec, s[64:65]
	s_waitcnt vmcnt(14)
	v_add_u32_e32 v16, 0xb0, v200
	v_lshlrev_b32_e32 v18, 16, v84
	v_and_b32_e32 v19, 0xffff0000, v84
	s_waitcnt lgkmcnt(0)
	v_lshlrev_b32_e32 v17, 6, v16
	v_pk_fma_f32 v[12:13], v[192:193], v[12:13], v[18:19]
	v_lshlrev_b32_e32 v20, 16, v85
	v_and_b32_e32 v21, 0xffff0000, v85
	v_and_or_b32 v17, v17, s86, v210
	v_pk_mul_f32 v[18:19], v[12:13], v[12:13]
	v_pk_fma_f32 v[14:15], v[192:193], v[14:15], v[20:21]
	v_lshlrev_b32_e32 v22, 16, v86
	v_pk_mul_f32 v[20:21], v[14:15], v[14:15]
	v_and_b32_e32 v23, 0xffff0000, v86
	v_lshlrev_b32_e32 v220, 1, v17
	v_add_f32_e32 v17, v18, v19
	v_pk_fma_f32 v[22:23], v[192:193], v[8:9], v[22:23]
	v_lshlrev_b32_e32 v8, 16, v87
	v_and_b32_e32 v9, 0xffff0000, v87
	v_add_f32_e32 v17, v20, v17
	v_pk_mul_f32 v[24:25], v[22:23], v[22:23]
	v_pk_fma_f32 v[26:27], v[192:193], v[10:11], v[8:9]
	v_cvt_pk_bf16_f32 v8, v12, v13
	v_lshl_add_u64 v[12:13], s[18:19], 0, v[220:221]
	v_add_f32_e32 v17, v21, v17
	v_cvt_pk_bf16_f32 v9, v14, v15
	v_cvt_pk_bf16_f32 v10, v22, v23
	v_cvt_pk_bf16_f32 v11, v26, v27
	v_lshl_add_u64 v[12:13], v[12:13], 0, v[198:199]
	v_add_f32_e32 v17, v24, v17
	v_pk_mul_f32 v[28:29], v[26:27], v[26:27]
	global_store_dwordx4 v[12:13], v[8:11], off
	v_add_f32_e32 v17, v25, v17
	v_add_f32_e32 v17, v28, v17
	v_lshlrev_b32_e32 v8, 16, v80
	v_and_b32_e32 v9, 0xffff0000, v80
	v_pk_fma_f32 v[4:5], v[192:193], v[4:5], v[8:9]
	v_lshlrev_b32_e32 v10, 16, v81
	v_pk_mul_f32 v[8:9], v[4:5], v[4:5]
	v_and_b32_e32 v11, 0xffff0000, v81
	v_add_f32_e32 v17, v29, v17
	v_pk_fma_f32 v[6:7], v[192:193], v[6:7], v[10:11]
	v_add_f32_e32 v8, v8, v17
	v_pk_mul_f32 v[10:11], v[6:7], v[6:7]
	v_lshlrev_b32_e32 v12, 16, v82
	v_and_b32_e32 v13, 0xffff0000, v82
	v_add_f32_e32 v8, v9, v8
	v_pk_fma_f32 v[12:13], v[192:193], v[0:1], v[12:13]
	v_add_f32_e32 v8, v10, v8
	v_pk_mul_f32 v[0:1], v[12:13], v[12:13]
	v_lshlrev_b32_e32 v14, 16, v83
	v_and_b32_e32 v15, 0xffff0000, v83
	v_add_f32_e32 v8, v11, v8
	v_pk_fma_f32 v[14:15], v[192:193], v[2:3], v[14:15]
	v_add_f32_e32 v0, v0, v8
	v_pk_mul_f32 v[2:3], v[14:15], v[14:15]
	v_add_f32_e32 v0, v1, v0
	v_add_f32_e32 v0, v2, v0
	v_add_f32_e32 v8, v3, v0
	v_cvt_pk_bf16_f32 v0, v4, v5
	v_lshl_add_u64 v[4:5], s[20:21], 0, v[220:221]
	v_cvt_pk_bf16_f32 v1, v6, v7
	v_cvt_pk_bf16_f32 v2, v12, v13
	v_cvt_pk_bf16_f32 v3, v14, v15
	v_lshl_add_u64 v[4:5], v[4:5], 0, v[198:199]
	global_store_dwordx4 v[4:5], v[0:3], off
	ds_bpermute_b32 v0, v209, v8
	s_waitcnt lgkmcnt(0)
	v_add_f32_e32 v0, v8, v0
	ds_bpermute_b32 v1, v208, v0
	s_and_saveexec_b64 s[18:19], vcc
	s_cbranch_execz .LBB0_1341
	v_ashrrev_i32_e32 v17, 31, v16
	v_lshlrev_b64 v[2:3], 6, v[16:17]
	v_lshl_add_u64 v[2:3], s[10:11], 0, v[2:3]
	v_lshl_add_u64 v[2:3], s[16:17], 2, v[2:3]
	s_lshl_b32 s30, s52, 2
	v_lshl_add_u64 v[2:3], v[2:3], 0, s[30:31]
	s_waitcnt lgkmcnt(0)
	v_add_f32_e32 v0, v0, v1
	global_store_dword v[2:3], v0, off
